# v37 + out phase mLSTM tail: barrier before the V-tile loads moved after them
# speedup vs baseline: 1.0075x; 1.0039x over previous
; #define LAS __attribute__((address_space(3)))
; DI bf16_t f2bf(float f) { return (bf16_t)cvt_pk_bf16(f, 0.f); }
; DI int crow(int i, int hh) { return (i & 3) + 8 * (i >> 2) + 4 * hh; }
; #define MFMA32(a, b, c) __builtin_amdgcn_mfma_f32_32x32x16_bf16((a), (b), (c), 0, 0, 0)
; template <int BR> DI void out_item(PARAMS P, int l, int cid, int h, LAS unsigned char* lds, int wave, int lane) {
;     ...
;     if (BR == 1) {
; #pragma unroll
;         for (int i = 0; i < 16; ++i) o[i] *= __expf(mp - fmaxf(mp, Gl[32 * tt + crow(i, hh)]));
;     }
;     if (wave < 4) {
;         const int ts = wave >> 1, ss = wave & 1; f32x16 p;
; #pragma unroll
;         for (int i = 0; i < 16; ++i) p[i] = 0.f;
;         if (ss <= ts) {
; #pragma unroll
;             for (int ks = 0; ks < NKS; ++ks) {
;                 const bf16x8 a = *(const bf16x8*)(Q + (size_t)(32 * ts + r) * QW + 16 * ks + 8 * hh), b = *(const bf16x8*)(K + (size_t)(32 * ss + r) * QW + 16 * ks + 8 * hh);
;                 p = MFMA32(a, b, p);
;             }
;         }
;         const int s = 32 * ss + r; float as = 0.f; if (BR == 1) as = Al[s];
; #pragma unroll
;         for (int i = 0; i < 16; ++i) { const int t = 32 * ts + crow(i, hh); float v = 0.f;
;             if (s <= t) { v = p[i]; if (BR == 1) v *= __expf(as - fmaxf(mp, Gl[t])); }
;             Pl[t * 72 + s] = f2bf(v); }
;     }
;     __syncthreads();
; #pragma unroll
;     for (int ks = 0; ks < 4; ++ks) {
;         const bf16x8 a = *(const LAS bf16x8*)(Pl + (32 * tt + r) * 72 + 16 * ks + 8 * hh); bf16x8 b;
; #pragma unroll
;         for (int j = 0; j < 8; ++j) b[j] = (short)V[(size_t)(16 * ks + 8 * hh + j) * 512 + 32 * vt + r];
;         o = MFMA32(a, b, o);
;     }
.LBB0_506:
	s_lshl_b64 s[52:53], s[52:53], 1
	v_readlane_b32 s12, v254, 39
	s_add_u32 s20, s12, s52
	v_readlane_b32 s12, v254, 27
	s_addc_u32 s21, s12, s53
	s_lshl_b32 s12, s48, 1
	s_add_u32 s20, s20, s12
	s_addc_u32 s21, s21, 0
	v_readlane_b32 s49, v254, 31
	s_add_u32 s49, s49, s52
	v_readlane_b32 vcc_lo, v254, 32
	s_addc_u32 vcc_hi, vcc_lo, s53
	s_add_u32 vcc_lo, s49, s12
	s_addc_u32 vcc_hi, vcc_hi, 0
	s_waitcnt lgkmcnt(14)
	v_lshlrev_b32_e32 v32, 1, v60
	s_waitcnt lgkmcnt(2)
	v_max_f32_e32 v20, v42, v42
	v_max_f32_e32 v21, v43, v43
	v_max_f32_e32 v22, v44, v44
	s_waitcnt lgkmcnt(0)
	v_lshl_add_u64 v[24:25], vcc, 0, v[32:33]
	global_load_ushort v42, v32, vcc
	global_load_ushort v43, v32, vcc offset:1024
	global_load_ushort v44, v32, vcc offset:2048
	s_nop 0
	global_load_ushort v32, v32, vcc offset:3072
	s_movk_i32 s49, 0x1000
	v_add_co_u32_e32 v26, vcc, s49, v24
	s_movk_i32 s49, 0x4000
	s_nop 0
	v_addc_co_u32_e32 v27, vcc, 0, v25, vcc
	v_add_co_u32_e32 v28, vcc, s49, v24
	s_movk_i32 s49, 0x5000
	s_nop 0
	v_addc_co_u32_e32 v29, vcc, 0, v25, vcc
	v_add_co_u32_e32 v30, vcc, s49, v24
	v_max_f32_e32 v17, v47, v47
	v_max_f32_e32 v18, v48, v48
	v_max_f32_e32 v19, v49, v49
	v_max_f32_e32 v23, v45, v45
	v_addc_co_u32_e32 v31, vcc, 0, v25, vcc
	global_load_ushort v45, v[26:27], off
	global_load_ushort v47, v[26:27], off offset:2048
	global_load_ushort v48, v[26:27], off offset:3072
	global_load_ushort v49, v[26:27], off offset:1024
	global_load_ushort v71, v[28:29], off offset:1024
	global_load_ushort v81, v[28:29], off offset:2048
	global_load_ushort v82, v[28:29], off offset:3072
	global_load_ushort v83, v[30:31], off offset:-4096
	global_load_ushort v84, v[30:31], off
	global_load_ushort v85, v[30:31], off offset:1024
	global_load_ushort v86, v[30:31], off offset:2048
	global_load_ushort v87, v[30:31], off offset:3072
	s_mov_b32 s49, 0x8000
	v_add_co_u32_e32 v26, vcc, s49, v24
	s_mov_b32 s49, 0x9000
	s_nop 0
	v_addc_co_u32_e32 v27, vcc, 0, v25, vcc
	v_add_co_u32_e32 v28, vcc, s49, v24
	v_max_f32_e32 v16, v46, v46
	s_nop 0
	v_addc_co_u32_e32 v29, vcc, 0, v25, vcc
	global_load_ushort v88, v[28:29], off offset:-4096
	global_load_ushort v89, v[28:29], off
	global_load_ushort v90, v[28:29], off offset:1024
	global_load_ushort v91, v[28:29], off offset:2048
	global_load_ushort v92, v[28:29], off offset:3072
	global_load_ushort v93, v[26:27], off offset:2048
	global_load_ushort v94, v[26:27], off offset:3072
	global_load_ushort v95, v[26:27], off offset:1024
	v_max_f32_e32 v46, v79, v79
	v_max_f32_e32 v26, v38, v38
	v_max_f32_e32 v27, v39, v39
	v_max_f32_e32 v28, v40, v40
	v_max_f32_e32 v29, v41, v41
	v_max_f32_e32 v26, v46, v26
	v_max_f32_e32 v27, v46, v27
	v_max_f32_e32 v28, v46, v28
	v_max_f32_e32 v29, v46, v29
	v_sub_f32_e32 v26, v79, v26
	v_sub_f32_e32 v27, v79, v27
	v_sub_f32_e32 v28, v79, v28
	v_sub_f32_e32 v29, v79, v29
	v_mul_f32_e32 v26, 0x3fb8aa3b, v26
	v_mul_f32_e32 v27, 0x3fb8aa3b, v27
	v_mul_f32_e32 v28, 0x3fb8aa3b, v28
	v_mul_f32_e32 v29, 0x3fb8aa3b, v29
	v_exp_f32_e32 v26, v26
	v_exp_f32_e32 v28, v28
	v_exp_f32_e32 v29, v29
	v_exp_f32_e32 v27, v27
	v_max_f32_e32 v34, v34, v34
	v_max_f32_e32 v35, v35, v35
	v_max_f32_e32 v36, v36, v36
	v_max_f32_e32 v37, v37, v37
	v_pk_mul_f32 v[10:11], v[10:11], v[28:29]
	v_pk_mul_f32 v[8:9], v[8:9], v[26:27]
	s_barrier
	ds_read_b128 v[26:29], v75
	v_max_f32_e32 v16, v46, v16
	v_max_f32_e32 v17, v46, v17
	v_max_f32_e32 v18, v46, v18
	v_max_f32_e32 v19, v46, v19
	v_max_f32_e32 v20, v46, v20
	v_max_f32_e32 v21, v46, v21
	v_max_f32_e32 v22, v46, v22
	v_max_f32_e32 v23, v46, v23
	v_max_f32_e32 v34, v46, v34
	v_max_f32_e32 v35, v46, v35
	v_max_f32_e32 v36, v46, v36
	v_max_f32_e32 v37, v46, v37
	v_sub_f32_e32 v16, v79, v16
	v_sub_f32_e32 v17, v79, v17
	v_sub_f32_e32 v18, v79, v18
	v_sub_f32_e32 v19, v79, v19
	v_sub_f32_e32 v20, v79, v20
	v_sub_f32_e32 v21, v79, v21
	v_sub_f32_e32 v22, v79, v22
	v_sub_f32_e32 v23, v79, v23
	v_sub_f32_e32 v34, v79, v34
	v_sub_f32_e32 v35, v79, v35
	v_sub_f32_e32 v36, v79, v36
	v_sub_f32_e32 v37, v79, v37
	v_mul_f32_e32 v16, 0x3fb8aa3b, v16
	v_mul_f32_e32 v17, 0x3fb8aa3b, v17
	v_mul_f32_e32 v18, 0x3fb8aa3b, v18
	v_mul_f32_e32 v19, 0x3fb8aa3b, v19
	v_mul_f32_e32 v20, 0x3fb8aa3b, v20
	v_mul_f32_e32 v21, 0x3fb8aa3b, v21
	v_mul_f32_e32 v22, 0x3fb8aa3b, v22
	v_mul_f32_e32 v23, 0x3fb8aa3b, v23
	v_mul_f32_e32 v34, 0x3fb8aa3b, v34
	v_mul_f32_e32 v35, 0x3fb8aa3b, v35
	v_mul_f32_e32 v36, 0x3fb8aa3b, v36
	v_mul_f32_e32 v37, 0x3fb8aa3b, v37
	v_exp_f32_e32 v16, v16
	v_exp_f32_e32 v17, v17
	v_exp_f32_e32 v18, v18
	v_exp_f32_e32 v19, v19
	v_exp_f32_e32 v20, v20
	v_exp_f32_e32 v21, v21
	v_exp_f32_e32 v22, v22
	v_exp_f32_e32 v23, v23
	v_exp_f32_e32 v34, v34
	v_exp_f32_e32 v36, v36
	v_exp_f32_e32 v37, v37
	v_exp_f32_e32 v35, v35
	v_pk_mul_f32 v[6:7], v[6:7], v[22:23]
	v_pk_mul_f32 v[4:5], v[4:5], v[20:21]
	v_pk_mul_f32 v[14:15], v[14:15], v[36:37]
	v_pk_mul_f32 v[12:13], v[12:13], v[34:35]
	v_pk_mul_f32 v[2:3], v[2:3], v[18:19]
	v_pk_mul_f32 v[0:1], v[0:1], v[16:17]
	s_waitcnt vmcnt(17)
	v_perm_b32 v19, v48, v47, s26
	s_waitcnt vmcnt(16)
	v_perm_b32 v18, v49, v45, s26
	v_perm_b32 v17, v32, v44, s26
	v_perm_b32 v16, v43, v42, s26
	ds_read_b128 v[20:23], v75 offset:32
	s_mov_b32 s49, 0xc000
	s_waitcnt lgkmcnt(1)
	v_mfma_f32_32x32x16_bf16 v[0:15], v[26:29], v[16:19], v[0:15]
	s_waitcnt vmcnt(8)
	v_perm_b32 v19, v87, v86, s26
	v_perm_b32 v18, v85, v84, s26
	v_perm_b32 v17, v82, v81, s26
	v_perm_b32 v16, v71, v83, s26
	v_add_co_u32_e32 v30, vcc, s49, v24
	s_mov_b32 s49, 0xd000
	s_waitcnt lgkmcnt(0)
; #define LAS __attribute__((address_space(3)))
; DI float bf2f(bf16_t v) { return __uint_as_float((unsigned)v << 16); }
; DI int crow(int i, int hh) { return (i & 3) + 8 * (i >> 2) + 4 * hh; }
; #define MFMA32(a, b, c) __builtin_amdgcn_mfma_f32_32x32x16_bf16((a), (b), (c), 0, 0, 0)
; template <int BR> DI void out_item(PARAMS P, int l, int cid, int h, LAS unsigned char* lds, int wave, int lane) {
;     ...
; #pragma unroll
;     for (int ks = 0; ks < 4; ++ks) {
;         const bf16x8 a = *(const LAS bf16x8*)(Pl + (32 * tt + r) * 72 + 16 * ks + 8 * hh); bf16x8 b;
; #pragma unroll
;         for (int j = 0; j < 8; ++j) b[j] = (short)V[(size_t)(16 * ks + 8 * hh + j) * 512 + 32 * vt + r];
;         o = MFMA32(a, b, o);
;     }
; #pragma unroll
;     for (int i = 0; i < 16; ++i) Ol[(32 * tt + crow(i, hh)) * 132 + 32 * vt + r] = o[i];
;     __syncthreads();
;     {
;         const int t = tid >> 3, seg = tid & 7; float ov[16];
; #pragma unroll
;         for (int e = 0; e < 16; ++e) ov[e] = Ol[t * 132 + 16 * seg + e];
;         const bf16_t* gp = GT + (size_t)t * 512 + 16 * seg;
;         f32x4 g0, g1, g2, g3; unpack8(*(const u32x4*)gp, g0, g1); unpack8(*(const u32x4*)(gp + 8), g2, g3);
;         const float gate[16] = {g0[0], g0[1], g0[2], g0[3], g1[0], g1[1], g1[2], g1[3], g2[0], g2[1], g2[2], g2[3], g3[0], g3[1], g3[2], g3[3]};
;         float outv[16];
;         if (BR == 1) {
;             float ps = 0.f;
; #pragma unroll
;             for (int e = 0; e < 8; ++e) ps += bf2f(Pl[t * 72 + 8 * seg + e]);
;             const float* np = (const float*)(P.ws + WS_NP) + (size_t)(cid * 4 + h) * 128 + 16 * seg; const bf16_t* qp = Q + (size_t)t * QW + 16 * seg; float qn = 0.f;
; #pragma unroll
;             for (int e = 0; e < 16; ++e) qn += bf2f(qp[e]) * np[e];
;             ps += __shfl_xor(ps, 1); ps += __shfl_xor(ps, 2); ps += __shfl_xor(ps, 4);
;             qn += __shfl_xor(qn, 1); qn += __shfl_xor(qn, 2); qn += __shfl_xor(qn, 4);
	v_mfma_f32_32x32x16_bf16 v[0:15], v[20:23], v[16:19], v[0:15]
	ds_read_b128 v[16:19], v75 offset:64
	v_addc_co_u32_e32 v31, vcc, 0, v25, vcc
	v_add_co_u32_e32 v24, vcc, s49, v24
	s_waitcnt vmcnt(3)
	v_perm_b32 v23, v92, v91, s26
	v_addc_co_u32_e32 v25, vcc, 0, v25, vcc
	v_perm_b32 v22, v90, v89, s26
	s_waitcnt vmcnt(1)
	v_perm_b32 v21, v94, v93, s26
	s_waitcnt vmcnt(0)
	v_perm_b32 v20, v95, v88, s26
	global_load_ushort v38, v[30:31], off offset:3072
	global_load_ushort v28, v[24:25], off offset:-4096
	global_load_ushort v29, v[24:25], off
	global_load_ushort v32, v[24:25], off offset:2048
	global_load_ushort v34, v[24:25], off offset:3072
	global_load_ushort v35, v[24:25], off offset:1024
	global_load_ushort v36, v[30:31], off offset:1024
	s_waitcnt lgkmcnt(0)
	v_mfma_f32_32x32x16_bf16 v[0:15], v[16:19], v[20:23], v[0:15]
	global_load_ushort v16, v[30:31], off offset:2048
	ds_read_b128 v[24:27], v75 offset:96
	s_lshl_b64 s[8:9], s[8:9], 9
	v_readlane_b32 s49, v254, 34
	s_add_u32 s8, s49, s8
	v_readlane_b32 s49, v254, 35
	s_addc_u32 s9, s49, s9
	s_waitcnt vmcnt(3)
	v_perm_b32 v19, v34, v32, s26
	s_waitcnt vmcnt(2)
	v_perm_b32 v18, v35, v29, s26
	s_waitcnt vmcnt(0)
	v_perm_b32 v17, v38, v16, s26
	v_perm_b32 v16, v36, v28, s26
	s_waitcnt lgkmcnt(0)
	s_nop 0
	v_mfma_f32_32x32x16_bf16 v[0:15], v[24:27], v[16:19], v[0:15]
	v_add_u32_e32 v16, 0x2400, v78
	s_nop 10
	ds_write2_b32 v16, v0, v1 offset1:132
	v_add_u32_e32 v0, 0x2800, v78
	ds_write2_b32 v0, v2, v3 offset0:8 offset1:140
	v_add_u32_e32 v0, 0x3400, v78
	ds_write2_b32 v0, v4, v5 offset0:32 offset1:164
	v_add_u32_e32 v0, 0x3800, v78
	ds_write2_b32 v0, v6, v7 offset0:40 offset1:172
	v_add_u32_e32 v0, 0x4400, v78
	ds_write2_b32 v0, v8, v9 offset0:64 offset1:196
	v_add_u32_e32 v0, 0x4800, v78
	ds_write2_b32 v0, v10, v11 offset0:72 offset1:204
	v_add_u32_e32 v0, 0x5400, v78
	ds_write2_b32 v0, v12, v13 offset0:96 offset1:228
	v_add_u32_e32 v0, 0x5800, v78
	ds_write2_b32 v0, v14, v15 offset0:104 offset1:236
	v_ashrrev_i32_e32 v14, 3, v80
	v_ashrrev_i32_e32 v15, 31, v14
	v_and_b32_e32 v2, 7, v80
	v_lshlrev_b64 v[12:13], 10, v[14:15]
	v_lshlrev_b32_e32 v32, 5, v2
	v_lshl_add_u64 v[0:1], s[6:7], 0, v[12:13]
	v_lshl_add_u64 v[0:1], v[0:1], 0, v[32:33]
	s_waitcnt lgkmcnt(0)
	s_barrier
	v_lshlrev_b32_e32 v34, 6, v2
	global_load_dwordx3 v[88:90], v[0:1], off
	global_load_dwordx4 v[8:11], v34, s[8:9]
	global_load_dwordx4 v[36:39], v34, s[8:9] offset:16
	global_load_dwordx4 v[40:43], v34, s[8:9] offset:32
	global_load_ushort v15, v[0:1], off offset:12
	global_load_dwordx4 v[80:83], v[0:1], off offset:14
	global_load_dwordx4 v[84:87], v34, s[8:9] offset:48
	global_load_ushort v35, v[0:1], off offset:30
	s_movk_i32 s6, 0x90
	v_lshlrev_b32_e32 v0, 4, v2
	v_mul_lo_u32 v1, v14, s6
	v_add3_u32 v0, 0, v1, v0
	ds_read_b128 v[16:19], v0
	v_lshl_add_u64 v[0:1], s[20:21], 0, v[12:13]
	v_lshl_add_u64 v[4:5], v[0:1], 0, v[32:33]
	global_load_dwordx4 v[0:3], v[4:5], off
	s_nop 0
	global_load_dwordx4 v[4:7], v[4:5], off offset:16
	v_readlane_b32 s6, v254, 58
	s_waitcnt lgkmcnt(0)
	v_lshlrev_b32_e32 v26, 16, v17
	v_and_b32_e32 v24, 0xffff0000, v17
	v_lshlrev_b32_e32 v44, 16, v16
	v_and_b32_e32 v28, 0xffff0000, v16
	v_lshlrev_b32_e32 v22, 16, v18
	v_and_b32_e32 v20, 0xffff0000, v18
	v_lshlrev_b32_e32 v18, 16, v19
	v_and_b32_e32 v16, 0xffff0000, v19
	v_readlane_b32 s7, v254, 59
	s_waitcnt vmcnt(9)
	v_lshlrev_b32_e32 v17, 16, v88
	s_waitcnt vmcnt(8)
	v_mov_b32_e32 v30, v9
	v_mov_b32_e32 v31, v10
	v_fma_f32 v17, v8, v17, 0
	v_and_b32_e32 v8, 0xffff0000, v88
	v_lshlrev_b32_e32 v9, 16, v89
	v_pk_mul_f32 v[8:9], v[30:31], v[8:9]
	v_mov_b32_e32 v10, v11
	v_add_f32_e32 v8, v17, v8
	s_waitcnt vmcnt(7)
	v_mov_b32_e32 v11, v36
	v_add_f32_e32 v17, v8, v9
	v_and_b32_e32 v8, 0xffff0000, v89
	v_lshlrev_b32_e32 v9, 16, v90
	v_pk_mul_f32 v[8:9], v[10:11], v[8:9]
	v_mov_b32_e32 v36, v37
	v_add_f32_e32 v8, v17, v8
	v_mov_b32_e32 v37, v38
	v_add_f32_e32 v10, v8, v9
	v_and_b32_e32 v8, 0xffff0000, v90
	s_waitcnt vmcnt(5)
	v_lshlrev_b32_e32 v9, 16, v15
	v_pk_mul_f32 v[8:9], v[36:37], v[8:9]
	v_mov_b32_e32 v38, v39
	v_add_f32_e32 v8, v10, v8
	v_mov_b32_e32 v39, v40
	v_add_f32_e32 v10, v8, v9
	s_waitcnt vmcnt(4)
	v_and_b32_e32 v9, 0xffff0000, v80
	v_lshlrev_b32_e32 v8, 16, v80
	v_pk_mul_f32 v[8:9], v[38:39], v[8:9]
	v_add_f32_e32 v30, 0, v44
	v_add_f32_e32 v8, v10, v8
	v_add_f32_e32 v29, v8, v9
	v_lshlrev_b32_e32 v8, 16, v81
	v_mul_f32_e32 v31, v41, v8
	v_and_b32_e32 v8, 0xffff0000, v81
	v_mul_f32_e32 v27, v42, v8
	v_lshlrev_b32_e32 v8, 16, v82
	v_mul_f32_e32 v25, v43, v8
	v_and_b32_e32 v8, 0xffff0000, v82
	s_waitcnt vmcnt(3)
	v_mul_f32_e32 v23, v84, v8
	v_lshlrev_b32_e32 v8, 16, v83
	v_mul_f32_e32 v21, v85, v8
	v_and_b32_e32 v8, 0xffff0000, v83
	v_mul_f32_e32 v19, v86, v8
	s_waitcnt vmcnt(2)
	v_lshlrev_b32_e32 v8, 16, v35
	v_mul_f32_e32 v17, v87, v8
	v_add_u32_e32 v8, s56, v14
	v_ashrrev_i32_e32 v9, 31, v8
	v_lshlrev_b64 v[8:9], 10, v[8:9]
	v_lshl_add_u64 v[8:9], s[6:7], 0, v[8:9]
	v_lshl_add_u64 v[8:9], v[8:9], 0, s[12:13]
	v_lshl_add_u64 v[36:37], v[8:9], 0, v[32:33]
	global_load_dwordx4 v[8:11], v[36:37], off offset:16
	v_pk_add_f32 v[28:29], v[30:31], v[28:29]
	v_and_b32_e32 v35, 64, v235
	v_pk_add_f32 v[26:27], v[28:29], v[26:27]
	v_xor_b32_e32 v15, 1, v235
	v_pk_add_f32 v[24:25], v[26:27], v[24:25]
	v_add_u32_e32 v35, 64, v35
	v_pk_add_f32 v[22:23], v[24:25], v[22:23]
	v_cmp_lt_i32_e32 vcc, v15, v35
	v_pk_add_f32 v[20:21], v[22:23], v[20:21]
	s_waitcnt vmcnt(1)
; __device__ __forceinline__ unsigned cvt_pk_bf16(float lo, float hi) { const f32x2_cv v = {lo, hi}; const bf16x2_cv b = __builtin_convertvector(v, bf16x2_cv); return __builtin_bit_cast(unsigned, b); }
; DI float bf2f(bf16_t v) { return __uint_as_float((unsigned)v << 16); }
; template <int BR> DI void out_item(PARAMS P, int l, int cid, int h, LAS unsigned char* lds, int wave, int lane) {
;     ...
;         if (BR == 1) {
;             float ps = 0.f;
; #pragma unroll
;             for (int e = 0; e < 8; ++e) ps += bf2f(Pl[t * 72 + 8 * seg + e]);
;             const float* np = (const float*)(P.ws + WS_NP) + (size_t)(cid * 4 + h) * 128 + 16 * seg; const bf16_t* qp = Q + (size_t)t * QW + 16 * seg; float qn = 0.f;
; #pragma unroll
;             for (int e = 0; e < 16; ++e) qn += bf2f(qp[e]) * np[e];
;             ps += __shfl_xor(ps, 1); ps += __shfl_xor(ps, 2); ps += __shfl_xor(ps, 4);
;             qn += __shfl_xor(qn, 1); qn += __shfl_xor(qn, 2); qn += __shfl_xor(qn, 4);
;             const float mg = fmaxf(mp, Gl[t]), den = ps + __expf(mp - mg) * qn, mt = Bl[t] + mg, dd = fmaxf(fabsf(den), __expf(-mt)), inv = 1.f / dd;
; #pragma unroll
;             for (int e = 0; e < 16; ++e) ov[e] *= inv;
;         }
;         float sq = 0.f;
; #pragma unroll
;         for (int e = 0; e < 16; ++e) sq += ov[e] * ov[e];
;         sq += __shfl_xor(sq, 1); sq += __shfl_xor(sq, 2); sq += __shfl_xor(sq, 4);
;         const float rs = rsqrtf(sq * (1.f / 128.f) + EPS);
;         if (BR == 1) {
;             const bf16_t* cp = gb + (size_t)CP_CC * G0ROWS + (size_t)(row0 + t) * 512 + h * 128 + 16 * seg; const float* sk = P.in[18] + l * 512 + h * 128 + 16 * seg;
; #pragma unroll
;             for (int e = 0; e < 16; ++e) outv[e] = gate[e] * (ov[e] * rs + sk[e] * bf2f(cp[e]));
;         } else {
; #pragma unroll
;             for (int e = 0; e < 16; ++e) outv[e] = ov[e] * rs * gate[e];
;         }
;         u32x4 w0, w1;
;         w0.x = cvt_pk_bf16(outv[0], outv[1]); w0.y = cvt_pk_bf16(outv[2], outv[3]); w0.z = cvt_pk_bf16(outv[4], outv[5]); w0.w = cvt_pk_bf16(outv[6], outv[7]);
;         w1.x = cvt_pk_bf16(outv[8], outv[9]); w1.y = cvt_pk_bf16(outv[10], outv[11]); w1.z = cvt_pk_bf16(outv[12], outv[13]); w1.w = cvt_pk_bf16(outv[14], outv[15]);
;         bf16_t* op = OB + (size_t)t * 512 + 16 * seg; *(u32x4*)op = w0; *(u32x4*)(op + 8) = w1;
;     }
;     __syncthreads();
	v_lshlrev_b32_e32 v48, 16, v7
	v_cndmask_b32_e32 v15, v235, v15, vcc
	v_pk_add_f32 v[18:19], v[20:21], v[18:19]
	v_lshlrev_b32_e32 v71, 2, v15
	v_pk_add_f32 v[16:17], v[18:19], v[16:17]
	ds_bpermute_b32 v18, v71, v16
	ds_bpermute_b32 v19, v71, v17
	v_xor_b32_e32 v15, 2, v235
	v_cmp_lt_i32_e32 vcc, v15, v35
	v_lshl_add_u32 v20, v14, 2, 0
	ds_read2st64_b32 v[20:21], v20 offset0:169 offset1:170
	v_cndmask_b32_e32 v15, v235, v15, vcc
	v_lshlrev_b32_e32 v108, 2, v15
	s_waitcnt lgkmcnt(1)
	v_pk_add_f32 v[16:17], v[16:17], v[18:19]
	v_xor_b32_e32 v15, 4, v235
	ds_bpermute_b32 v18, v108, v16
	ds_bpermute_b32 v19, v108, v17
	v_cmp_lt_i32_e32 vcc, v15, v35
	v_mul_lo_u32 v14, v14, s93
	v_add3_u32 v35, 0, v14, v34
	v_cndmask_b32_e32 v15, v235, v15, vcc
	v_lshlrev_b32_e32 v109, 2, v15
	s_waitcnt lgkmcnt(2)
	v_max_f32_e32 v15, v20, v20
	v_max_f32_e32 v15, v46, v15
	s_waitcnt lgkmcnt(0)
	v_pk_add_f32 v[22:23], v[16:17], v[18:19]
	v_sub_f32_e32 v16, v79, v15
	ds_bpermute_b32 v24, v109, v22
	ds_bpermute_b32 v25, v109, v23
	v_mul_f32_e32 v16, 0x3fb8aa3b, v16
	v_exp_f32_e32 v26, v16
	v_add_f32_e32 v15, v21, v15
	global_load_dwordx4 v[16:19], v[36:37], off
	v_mul_f32_e32 v15, 0xbfb8aa3b, v15
	v_exp_f32_e32 v15, v15
	s_waitcnt lgkmcnt(0)
	v_pk_add_f32 v[20:21], v[22:23], v[24:25]
	v_and_b32_e32 v49, 0xffff0000, v7
	v_fmac_f32_e32 v20, v21, v26
	v_max_f32_e64 v15, |v20|, v15
	v_div_scale_f32 v20, s[6:7], v15, v15, 1.0
	v_rcp_f32_e32 v21, v20
	s_lshl_b32 s6, s48, 2
	v_readlane_b32 s7, v254, 60
	s_add_u32 s6, s7, s6
	v_fma_f32 v14, -v20, v21, 1.0
	v_fmac_f32_e32 v21, v14, v21
	v_div_scale_f32 v14, vcc, 1.0, v15, 1.0
	v_mul_f32_e32 v22, v14, v21
	v_fma_f32 v23, -v20, v22, v14
	v_fmac_f32_e32 v22, v23, v21
	v_fma_f32 v14, -v20, v22, v14
	v_div_fmas_f32 v14, v14, v21, v22
	ds_read_b128 v[20:23], v35 offset:9216
	ds_read_b128 v[24:27], v35 offset:9232
	ds_read_b128 v[28:31], v35 offset:9264
	v_readlane_b32 s7, v254, 61
	s_addc_u32 s7, s7, 0
	v_div_fixup_f32 v14, v14, v15, 1.0
	ds_read_b128 v[40:43], v35 offset:9248
	s_waitcnt lgkmcnt(1)
	v_pk_mul_f32 v[84:85], v[30:31], v[14:15] op_sel_hi:[1,0]
	v_lshlrev_b32_e32 v88, 16, v6
	global_load_dwordx4 v[36:39], v34, s[6:7]
	global_load_dwordx4 v[44:47], v34, s[6:7] offset:16
	v_and_b32_e32 v89, 0xffff0000, v6
	v_pk_mul_f32 v[6:7], v[28:29], v[14:15] op_sel_hi:[1,0]
	global_load_dwordx4 v[28:31], v34, s[6:7] offset:48
	global_load_dwordx4 v[80:83], v34, s[6:7] offset:32
	v_lshlrev_b32_e32 v92, 16, v5
	v_and_b32_e32 v93, 0xffff0000, v5
	s_waitcnt lgkmcnt(0)
	v_pk_mul_f32 v[42:43], v[42:43], v[14:15] op_sel_hi:[1,0]
	v_lshlrev_b32_e32 v98, 16, v4
	v_and_b32_e32 v99, 0xffff0000, v4
	v_pk_mul_f32 v[4:5], v[40:41], v[14:15] op_sel_hi:[1,0]
	v_pk_mul_f32 v[26:27], v[26:27], v[14:15] op_sel_hi:[1,0]
	v_pk_mul_f32 v[24:25], v[24:25], v[14:15] op_sel_hi:[1,0]
	v_pk_mul_f32 v[22:23], v[22:23], v[14:15] op_sel_hi:[1,0]
	v_pk_mul_f32 v[14:15], v[20:21], v[14:15] op_sel_hi:[1,0]
	s_waitcnt vmcnt(5)
	v_and_b32_e32 v35, 0xffff0000, v10
	v_pk_mul_f32 v[20:21], v[14:15], v[14:15]
	v_lshlrev_b32_e32 v34, 16, v10
	v_pk_mul_f32 v[106:107], v[22:23], v[22:23]
	v_add_f32_e32 v10, v20, v21
	v_add_f32_e32 v10, v106, v10
	v_pk_mul_f32 v[104:105], v[24:25], v[24:25]
	v_add_f32_e32 v10, v107, v10
	v_add_f32_e32 v10, v104, v10
	v_pk_mul_f32 v[102:103], v[26:27], v[26:27]
	v_add_f32_e32 v10, v105, v10
	v_add_f32_e32 v10, v102, v10
	v_pk_mul_f32 v[40:41], v[4:5], v[4:5]
	v_add_f32_e32 v10, v103, v10
	v_add_f32_e32 v10, v40, v10
	v_pk_mul_f32 v[94:95], v[42:43], v[42:43]
	v_add_f32_e32 v10, v41, v10
	v_add_f32_e32 v10, v94, v10
	v_pk_mul_f32 v[90:91], v[6:7], v[6:7]
	v_add_f32_e32 v10, v95, v10
	v_add_f32_e32 v10, v90, v10
	v_pk_mul_f32 v[86:87], v[84:85], v[84:85]
	v_add_f32_e32 v10, v91, v10
	v_add_f32_e32 v10, v86, v10
	v_add_f32_e32 v10, v87, v10
	ds_bpermute_b32 v41, v71, v10
	v_lshlrev_b32_e32 v100, 16, v3
	v_and_b32_e32 v101, 0xffff0000, v3
	v_lshlrev_b32_e32 v40, 16, v2
	v_lshlrev_b32_e32 v90, 16, v0
	s_waitcnt lgkmcnt(0)
	v_add_f32_e32 v10, v10, v41
	v_and_b32_e32 v41, 0xffff0000, v2
	v_and_b32_e32 v91, 0xffff0000, v0
	v_readlane_b32 s6, v254, 62
	v_and_b32_e32 v97, 0xffff0000, v9
	v_lshlrev_b32_e32 v96, 16, v9
	s_waitcnt vmcnt(4)
	v_and_b32_e32 v21, 0xffff0000, v19
	v_lshlrev_b32_e32 v20, 16, v19
	ds_bpermute_b32 v19, v108, v10
	v_and_b32_e32 v3, 0xffff0000, v18
	v_lshlrev_b32_e32 v2, 16, v18
	v_lshlrev_b32_e32 v18, 16, v1
	v_lshlrev_b32_e32 v0, 16, v16
	s_waitcnt lgkmcnt(0)
	v_add_f32_e32 v10, v10, v19
	ds_bpermute_b32 v71, v109, v10
	v_and_b32_e32 v19, 0xffff0000, v1
	v_and_b32_e32 v9, 0xffff0000, v8
	v_lshlrev_b32_e32 v8, 16, v8
	v_and_b32_e32 v87, 0xffff0000, v17
	s_waitcnt lgkmcnt(0)
	v_add_f32_e32 v1, v10, v71
	v_fmamk_f32 v1, v1, 0x3c000000, v229
	v_mul_f32_e32 v10, 0x4b800000, v1
	v_cmp_gt_f32_e32 vcc, s81, v1
	v_lshlrev_b32_e32 v86, 16, v17
	s_add_u32 s6, s6, s52
	v_cndmask_b32_e32 v1, v1, v10, vcc
	v_rsq_f32_e32 v10, v1
	v_and_b32_e32 v1, 0xffff0000, v16
	v_readlane_b32 s7, v254, 63
	s_addc_u32 s7, s7, s53
	v_mul_f32_e32 v16, 0x45800000, v10
	v_cndmask_b32_e32 v10, v10, v16, vcc
	v_pk_mul_f32 v[14:15], v[14:15], v[10:11] op_sel_hi:[1,0]
	v_pk_mul_f32 v[4:5], v[4:5], v[10:11] op_sel_hi:[1,0]
	v_pk_mul_f32 v[16:17], v[24:25], v[10:11] op_sel_hi:[1,0]
	s_waitcnt vmcnt(3)
	v_pk_fma_f32 v[0:1], v[36:37], v[0:1], v[14:15]
	v_pk_mul_f32 v[14:15], v[22:23], v[10:11] op_sel_hi:[1,0]
	s_waitcnt vmcnt(2)
	v_pk_fma_f32 v[2:3], v[44:45], v[2:3], v[16:17]
	v_pk_fma_f32 v[14:15], v[38:39], v[86:87], v[14:15]
	s_waitcnt vmcnt(0)
	v_pk_fma_f32 v[4:5], v[80:81], v[8:9], v[4:5]
	v_pk_mul_f32 v[8:9], v[42:43], v[10:11] op_sel_hi:[1,0]
	v_pk_mul_f32 v[14:15], v[14:15], v[18:19]
	v_pk_mul_f32 v[16:17], v[26:27], v[10:11] op_sel_hi:[1,0]
	v_pk_fma_f32 v[8:9], v[82:83], v[96:97], v[8:9]
	v_and_b32_e32 v19, 0xffff0000, v11
	v_lshlrev_b32_e32 v18, 16, v11
	s_add_u32 s6, s6, s12
	v_pk_fma_f32 v[16:17], v[46:47], v[20:21], v[16:17]
	v_pk_mul_f32 v[4:5], v[4:5], v[98:99]
	v_pk_mul_f32 v[8:9], v[8:9], v[92:93]
	v_pk_mul_f32 v[6:7], v[6:7], v[10:11] op_sel_hi:[1,0]
	v_pk_mul_f32 v[18:19], v[30:31], v[18:19]
	s_addc_u32 s7, s7, 0
	v_pk_mul_f32 v[0:1], v[0:1], v[90:91]
	v_pk_mul_f32 v[2:3], v[2:3], v[40:41]
	v_pk_mul_f32 v[16:17], v[16:17], v[100:101]
	v_pk_fma_f32 v[6:7], v[28:29], v[34:35], v[6:7]
	v_pk_fma_f32 v[10:11], v[84:85], v[10:11], v[18:19] op_sel_hi:[1,0,1]
	v_cvt_pk_bf16_f32 v4, v4, v5
	v_cvt_pk_bf16_f32 v5, v8, v9
	v_lshl_add_u64 v[8:9], s[6:7], 0, v[12:13]
	v_pk_mul_f32 v[6:7], v[6:7], v[88:89]
	v_pk_mul_f32 v[10:11], v[10:11], v[48:49]
	v_cvt_pk_bf16_f32 v0, v0, v1
	v_cvt_pk_bf16_f32 v1, v14, v15
	v_cvt_pk_bf16_f32 v2, v2, v3
	v_cvt_pk_bf16_f32 v3, v16, v17
	v_lshl_add_u64 v[8:9], v[8:9], 0, v[32:33]
	s_mov_b64 s[6:7], 0
	v_cvt_pk_bf16_f32 v6, v6, v7
	v_cvt_pk_bf16_f32 v7, v10, v11
	global_store_dwordx4 v[8:9], v[0:3], off
	global_store_dwordx4 v[8:9], v[4:7], off offset:16
	s_barrier
